# v73 + attention row-max chain: dropped three re-canonicalising v_max x,x per softmax slice (values already v_max3/v_cndmask results), bit-identical
# speedup vs baseline: 1.0001x; 1.0001x over previous
; template <int N> __device__ __forceinline__ void psm_slice(f32x16& p0, f32x16& p1, float& m_reg, float& alpha, PsmSt& st) {
;     if constexpr (N == 0) { float c = fmaxf(p0[0], p0[1]);
; #pragma unroll
;         for (int r = 2; r < 16; r += 2) c = fmaxf(fmaxf(c, p0[r]), p0[r + 1]);
;         st.c0 = c; }
;     else if constexpr (N == 1) { float c = fmaxf(p1[0], p1[1]);
; #pragma unroll
;         for (int r = 2; r < 16; r += 2) c = fmaxf(fmaxf(c, p1[r]), p1[r + 1]);
;         st.c1 = c; }
;     else if constexpr (N == 2) { float pmax = fmaxf(st.c0, st.c1);
;         auto rr = __builtin_amdgcn_permlane32_swap(__float_as_uint(pmax), __float_as_uint(pmax), false, false); pmax = fmaxf(__uint_as_float(rr[0]), __uint_as_float(rr[1]));
;         const bool keep = __all(pmax - m_reg <= THR2);
;         st.mn = keep ? m_reg : fmaxf(m_reg, pmax); }
;     else if constexpr (N == 3) { alpha = __builtin_amdgcn_exp2f(m_reg - st.mn); m_reg = st.mn; }
;     else if constexpr (N < 8) { constexpr int r = 2 * (N - 4); p0[r] = __builtin_amdgcn_exp2f(p0[r] - st.mn); p0[r + 1] = __builtin_amdgcn_exp2f(p0[r + 1] - st.mn); }
;     else { constexpr int r = N; p0[r] = __builtin_amdgcn_exp2f(p0[r] - st.mn); }
; template <bool PSM, bool PRE> __device__ __forceinline__ void region_pv(f32x16* o, int vb, const bf16x8 (&pa)[4], f32x16& pn0, f32x16& pn1, float& m_reg, float& alpha, s16x4 (&l)[4], s16x4 (&h)[4]) {
;     PsmSt st;
;     if constexpr (!PRE) {
;     l[0] = tr_read<v_rd_off(0, 0, 0)>(vb); h[0] = tr_read<v_rd_off(0, 0, 1)>(vb); l[1] = tr_read<v_rd_off(0, 1, 0)>(vb); h[1] = tr_read<v_rd_off(0, 1, 1)>(vb);
;     l[2] = tr_read<v_rd_off(0, 2, 0)>(vb); h[2] = tr_read<v_rd_off(0, 2, 1)>(vb); l[3] = tr_read<v_rd_off(0, 3, 0)>(vb); h[3] = tr_read<v_rd_off(0, 3, 1)>(vb);
;     SBAR(); }
;     sfor<0, 16>([&](auto n_) { constexpr int n = decltype(n_)::value, b = n >> 2, k = n & 3;
;         o[b] = __builtin_amdgcn_mfma_f32_32x32x16_bf16(pa[k], (bf16x8){l[k][0], l[k][1], l[k][2], l[k][3], h[k][0], h[k][1], h[k][2], h[k][3]}, o[b], 0, 0, 0);
;         if constexpr (b < 3) { l[k] = tr_read<v_rd_off((b + 1) & 3, k, 0)>(vb); h[k] = tr_read<v_rd_off((b + 1) & 3, k, 1)>(vb); }
;         if constexpr (PSM) psm_slice<n>(pn0, pn1, m_reg, alpha, st);
;         __builtin_amdgcn_sched_group_barrier(0x8, 1, 0); __builtin_amdgcn_sched_group_barrier(0x100, 2, 0);
;         SBAR();
;     });
.LBB0_624:
	s_waitcnt lgkmcnt(6)
	v_mfma_f32_32x32x16_bf16 v[0:15], v[64:67], v[100:103], v[0:15]
	v_max3_f32 v108, v110, v111, v112
	v_max3_f32 v108, v108, v113, v114
	ds_read_b64_tr_b16 v[100:101], v251 offset:512
	ds_read_b64_tr_b16 v[102:103], v251 offset:2560
	v_max3_f32 v108, v108, v115, v116
	v_max3_f32 v108, v108, v117, v118
	v_max3_f32 v108, v108, v119, v120
	v_max3_f32 v108, v108, v121, v122
	v_max3_f32 v108, v108, v123, v124
	s_waitcnt lgkmcnt(6)
	v_mfma_f32_32x32x16_bf16 v[0:15], v[68:71], v[126:129], v[0:15]
	v_max_f32_e32 v109, v81, v81
	v_max_f32_e32 v126, v80, v80
	v_max_f32_e32 v109, v126, v109
	v_max3_f32 v109, v109, v82, v83
	ds_read_b64_tr_b16 v[132:133], v251 offset:4608
	ds_read_b64_tr_b16 v[134:135], v251 offset:6656
	v_max3_f32 v109, v109, v84, v85
	v_max3_f32 v109, v109, v86, v87
	v_max3_f32 v109, v109, v88, v89
	v_max3_f32 v109, v109, v90, v91
	v_max3_f32 v109, v109, v92, v93
	v_max3_f32 v109, v109, v94, v95
	v_max3_f32 v108, v108, v125, v109
	v_mov_b32_e32 v109, v108
	s_waitcnt lgkmcnt(6)
	v_mfma_f32_32x32x16_bf16 v[0:15], v[72:75], v[104:107], v[0:15]
	v_permlane32_swap_b32_e32 v108, v109
	v_max_f32_e32 v108, v108, v109
	v_sub_f32_e32 v109, v108, v130
	ds_read_b64_tr_b16 v[104:105], v251 offset:8704
	ds_read_b64_tr_b16 v[106:107], v251 offset:10752
	v_cmp_ge_f32_e32 vcc, s33, v109
	s_cmp_eq_u64 vcc, exec
	s_cselect_b64 vcc, -1, 0
	v_max_f32_e32 v108, v130, v108
	v_cndmask_b32_e32 v252, v108, v130, vcc
	s_waitcnt lgkmcnt(6)
	v_mfma_f32_32x32x16_bf16 v[0:15], v[76:79], v[96:99], v[0:15]
	v_sub_f32_e32 v108, v130, v252
	ds_read_b64_tr_b16 v[96:97], v251 offset:12800
	ds_read_b64_tr_b16 v[98:99], v251 offset:14848
	v_exp_f32_e32 v227, v108
	s_waitcnt lgkmcnt(6)
	v_mfma_f32_32x32x16_bf16 v[48:63], v[64:67], v[100:103], v[48:63]
	v_sub_f32_e32 v108, v110, v252
	v_exp_f32_e32 v126, v108
	v_sub_f32_e32 v108, v111, v252
	ds_read_b64_tr_b16 v[100:101], v251 offset:1024
	ds_read_b64_tr_b16 v[102:103], v251 offset:3072
	v_exp_f32_e32 v127, v108
	s_waitcnt lgkmcnt(6)
	v_mfma_f32_32x32x16_bf16 v[48:63], v[68:71], v[132:135], v[48:63]
	v_sub_f32_e32 v112, v112, v252
	v_exp_f32_e32 v128, v112
	v_sub_f32_e32 v112, v113, v252
	ds_read_b64_tr_b16 v[108:109], v251 offset:5120
	ds_read_b64_tr_b16 v[110:111], v251 offset:7168
	v_exp_f32_e32 v129, v112
	s_waitcnt lgkmcnt(6)
	v_mfma_f32_32x32x16_bf16 v[48:63], v[72:75], v[104:107], v[48:63]
	v_sub_f32_e32 v112, v114, v252
	v_exp_f32_e32 v130, v112
	v_sub_f32_e32 v112, v115, v252
	ds_read_b64_tr_b16 v[104:105], v251 offset:9216
	ds_read_b64_tr_b16 v[106:107], v251 offset:11264
	v_exp_f32_e32 v131, v112
	s_waitcnt lgkmcnt(6)
	v_mfma_f32_32x32x16_bf16 v[48:63], v[76:79], v[96:99], v[48:63]
	v_sub_f32_e32 v112, v116, v252
	v_exp_f32_e32 v132, v112
	v_sub_f32_e32 v112, v117, v252
	ds_read_b64_tr_b16 v[96:97], v251 offset:13312
	ds_read_b64_tr_b16 v[98:99], v251 offset:15360
	v_exp_f32_e32 v133, v112
	s_waitcnt lgkmcnt(6)
	v_mfma_f32_32x32x16_bf16 v[32:47], v[64:67], v[100:103], v[32:47]
	v_sub_f32_e32 v112, v118, v252
	ds_read_b64_tr_b16 v[100:101], v251 offset:1536
	ds_read_b64_tr_b16 v[102:103], v251 offset:3584
	v_exp_f32_e32 v134, v112
	s_waitcnt lgkmcnt(6)
	v_mfma_f32_32x32x16_bf16 v[32:47], v[68:71], v[108:111], v[32:47]
	v_sub_f32_e32 v112, v119, v252
	ds_read_b64_tr_b16 v[108:109], v251 offset:5632
	ds_read_b64_tr_b16 v[110:111], v251 offset:7680
	v_exp_f32_e32 v135, v112
	s_waitcnt lgkmcnt(6)
	v_mfma_f32_32x32x16_bf16 v[32:47], v[72:75], v[104:107], v[32:47]
	v_sub_f32_e32 v112, v120, v252
	ds_read_b64_tr_b16 v[104:105], v251 offset:9728
	ds_read_b64_tr_b16 v[106:107], v251 offset:11776
	v_exp_f32_e32 v136, v112
	s_waitcnt lgkmcnt(6)
	v_mfma_f32_32x32x16_bf16 v[32:47], v[76:79], v[96:99], v[32:47]
	v_sub_f32_e32 v112, v121, v252
	ds_read_b64_tr_b16 v[96:97], v251 offset:13824
	ds_read_b64_tr_b16 v[98:99], v251 offset:15872
	v_exp_f32_e32 v137, v112
	s_waitcnt lgkmcnt(6)
	v_mfma_f32_32x32x16_bf16 v[16:31], v[64:67], v[100:103], v[16:31]
	v_sub_f32_e32 v64, v122, v252
	v_exp_f32_e32 v138, v64
	s_waitcnt lgkmcnt(4)
	v_mfma_f32_32x32x16_bf16 v[16:31], v[68:71], v[108:111], v[16:31]
	v_sub_f32_e32 v64, v123, v252
	v_exp_f32_e32 v139, v64
	s_waitcnt lgkmcnt(2)
	v_mfma_f32_32x32x16_bf16 v[16:31], v[72:75], v[104:107], v[16:31]
	v_sub_f32_e32 v64, v124, v252
	v_exp_f32_e32 v140, v64
	s_waitcnt lgkmcnt(0)
	v_mfma_f32_32x32x16_bf16 v[16:31], v[76:79], v[96:99], v[16:31]
	v_sub_f32_e32 v64, v125, v252
	v_exp_f32_e32 v141, v64
	v_cmp_gt_f32_e32 vcc, 1.0, v227
	s_cbranch_vccz .LBB0_628
	s_and_saveexec_b64 s[48:49], s[40:41]
	ds_write_b32 v215, v227 offset:128
	s_or_b64 exec, exec, s[48:49]
	s_waitcnt lgkmcnt(0)
	ds_read_b128 v[64:67], v250 offset:224
	ds_read_b128 v[68:71], v250 offset:192
	ds_read_b128 v[72:75], v250 offset:160
	ds_read_b128 v[76:79], v250 offset:128
	s_waitcnt lgkmcnt(3)
	v_pk_mul_f32 v[14:15], v[14:15], v[66:67]
	s_waitcnt lgkmcnt(2)
	v_pk_mul_f32 v[10:11], v[10:11], v[70:71]
	s_waitcnt lgkmcnt(1)
	v_pk_mul_f32 v[6:7], v[6:7], v[74:75]
	s_waitcnt lgkmcnt(0)
	v_pk_mul_f32 v[2:3], v[2:3], v[78:79]
	v_pk_mul_f32 v[12:13], v[12:13], v[64:65]
	v_pk_mul_f32 v[8:9], v[8:9], v[68:69]
	v_pk_mul_f32 v[4:5], v[4:5], v[72:73]
	v_pk_mul_f32 v[0:1], v[0:1], v[76:77]
	v_pk_mul_f32 v[62:63], v[62:63], v[66:67]
	v_pk_mul_f32 v[58:59], v[58:59], v[70:71]
	v_pk_mul_f32 v[54:55], v[54:55], v[74:75]
	v_pk_mul_f32 v[50:51], v[50:51], v[78:79]
	v_pk_mul_f32 v[60:61], v[60:61], v[64:65]
	v_pk_mul_f32 v[56:57], v[56:57], v[68:69]
	v_pk_mul_f32 v[52:53], v[52:53], v[72:73]
	v_pk_mul_f32 v[48:49], v[48:49], v[76:77]
	v_pk_mul_f32 v[46:47], v[46:47], v[66:67]
	v_pk_mul_f32 v[42:43], v[42:43], v[70:71]
	v_pk_mul_f32 v[38:39], v[38:39], v[74:75]
	v_pk_mul_f32 v[34:35], v[34:35], v[78:79]
	v_pk_mul_f32 v[44:45], v[44:45], v[64:65]
	v_pk_mul_f32 v[40:41], v[40:41], v[68:69]
	v_pk_mul_f32 v[36:37], v[36:37], v[72:73]
	v_pk_mul_f32 v[32:33], v[32:33], v[76:77]
	v_pk_mul_f32 v[30:31], v[30:31], v[66:67]
	v_pk_mul_f32 v[26:27], v[26:27], v[70:71]
	v_pk_mul_f32 v[22:23], v[22:23], v[74:75]
	v_pk_mul_f32 v[18:19], v[18:19], v[78:79]
	v_pk_mul_f32 v[28:29], v[28:29], v[64:65]
	v_pk_mul_f32 v[24:25], v[24:25], v[68:69]
	v_pk_mul_f32 v[20:21], v[20:21], v[72:73]
	v_pk_mul_f32 v[16:17], v[16:17], v[76:77]
	.p2align 6
; #define SBAR() __builtin_amdgcn_sched_barrier(0)
; template <int M> __device__ __forceinline__ void fin_slice(f32x16& p0, f32x16& p1, float mreg, float alpha, float& l_reg, FinSt& st, bf16x8 (&pa)[4]) {
;     if constexpr (M < 16) {
;         p1[M] = __builtin_amdgcn_exp2f(p1[M] - mreg);
;         if constexpr (M == 0) st.s0 = p0[0]; else st.s0 += p0[M];
;         if constexpr ((M & 1) == 0) st.c[M / 2] = cvt_pk_n(p0[M], p0[M + 1]);
;     } else if constexpr (M < 20) {
;         constexpr int k = M - 16;
;         if constexpr (k == 0) st.s1 = p1[0]; else st.s1 += p1[4 * k];
;         st.s1 += p1[4 * k + 1]; st.s1 += p1[4 * k + 2]; st.s1 += p1[4 * k + 3];
; template <bool FIN, bool PRE, int DM, class Dma> __device__ __forceinline__ void region_qk(f32x16& ps0, f32x16& ps1, const char* Ks, const bf16x8* qr, const char* qslot, const int (&kb)[4], ...
;     bf16x8 kf[2][2], qf[2]; FinSt st;
;     ...
;     QKT_RD(0, 0);
;     sfor<0, 12>([&](auto d_) { constexpr int d0 = decltype(d_)::value, cb = d0 & 1, nb = cb ^ 1;
;         if constexpr (d0 < 11) QKT_RD(d0 + 1, nb);
;         if constexpr (d0 == 0) ps0 = __builtin_amdgcn_mfma_f32_32x32x16_bf16(kf[cb][0], qf[cb], f32x16{}, 0, 0, 0);
;         else ps0 = __builtin_amdgcn_mfma_f32_32x32x16_bf16(kf[cb][0], qf[cb], ps0, 0, 0, 0);
;         if constexpr (FIN) fin_slice<2 * d0>(pf0, pf1, mreg, alpha, l_reg, st, pa);
;         if constexpr (PRE && d0 >= 10) { constexpr int k = 2 * (d0 - 10); l[k] = tr_read<v_rd_off(0, k, 0)>(vb); h[k] = tr_read<v_rd_off(0, k, 1)>(vb); }
;         __builtin_amdgcn_sched_group_barrier(0x100, 3, 0); __builtin_amdgcn_sched_group_barrier(0x8, 1, 0);
;         SBAR();
;         if constexpr (d0 == 0) ps1 = __builtin_amdgcn_mfma_f32_32x32x16_bf16(kf[cb][1], qf[cb], f32x16{}, 0, 0, 0);
;         else ps1 = __builtin_amdgcn_mfma_f32_32x32x16_bf16(kf[cb][1], qf[cb], ps1, 0, 0, 0);
;         if constexpr (FIN) fin_slice<2 * d0 + 1>(pf0, pf1, mreg, alpha, l_reg, st, pa);
;         if constexpr (PRE && d0 >= 10) { constexpr int k = 2 * (d0 - 10) + 1; l[k] = tr_read<v_rd_off(0, k, 0)>(vb); h[k] = tr_read<v_rd_off(0, k, 1)>(vb); }
;         if constexpr ((d0 & 1) == 0 && d0 < 10 && (DM == 1 || (DM == 2 && d0 >= 6))) dma(std::integral_constant<int, d0 / 2>{});
;         __builtin_amdgcn_sched_group_barrier(0x8, 1, 0);
;         SBAR();
;     });
.LBB0_628:
	s_waitcnt vmcnt(0)
	s_waitcnt lgkmcnt(0)
	s_barrier
	ds_read_b128 v[64:67], v242 offset:32768
	ds_read_b128 v[68:71], v242 offset:45056
	ds_read_b128 v[112:115], v244 offset:32768
	ds_read_b128 v[116:119], v244 offset:45056
	v_sub_f32_e32 v72, v80, v252
	v_exp_f32_e32 v194, v72
	v_cvt_pk_bf16_f32 v80, v126, v127
	s_waitcnt lgkmcnt(3)
	v_mfma_f32_32x32x16_bf16 v[96:111], v[64:67], v[186:189], 0
	s_waitcnt lgkmcnt(2)
	v_mfma_f32_32x32x16_bf16 v[64:79], v[68:71], v[186:189], 0
	s_add_u32 s48, s46, 1
	s_addc_u32 s49, s47, 0
	v_lshlrev_b64 v[120:121], v210, s[48:49]
	v_lshl_add_u64 v[120:121], v[120:121], 1, v[228:229]
	s_mov_b32 s12, m0
	s_mov_b32 m0, s66
	s_nop 0
	global_load_lds_dwordx4 v[120:121], off
	s_mov_b32 m0, s12
	v_sub_f32_e32 v81, v81, v252
	v_exp_f32_e32 v195, v81
	v_add_f32_e32 v81, v126, v127
	ds_read_b128 v[120:123], v246 offset:32768
	ds_read_b128 v[124:127], v246 offset:45056
	s_waitcnt lgkmcnt(3)
	v_mfma_f32_32x32x16_bf16 v[96:111], v[112:115], v[182:185], v[96:111]
	v_sub_f32_e32 v82, v82, v252
	v_exp_f32_e32 v196, v82
	v_add_f32_e32 v82, v128, v81
	v_cvt_pk_bf16_f32 v81, v128, v129
	s_waitcnt lgkmcnt(2)
	v_mfma_f32_32x32x16_bf16 v[64:79], v[116:119], v[182:185], v[64:79]
	v_sub_f32_e32 v83, v83, v252
	v_exp_f32_e32 v128, v83
	v_add_f32_e32 v82, v129, v82
	ds_read_b128 v[112:115], v248 offset:32768
	ds_read_b128 v[116:119], v248 offset:45056
	s_waitcnt lgkmcnt(3)
	v_mfma_f32_32x32x16_bf16 v[96:111], v[120:123], v[178:181], v[96:111]
	v_sub_f32_e32 v83, v84, v252
	v_exp_f32_e32 v129, v83
	v_add_f32_e32 v83, v130, v82
	v_cvt_pk_bf16_f32 v82, v130, v131
	s_waitcnt lgkmcnt(2)
	v_mfma_f32_32x32x16_bf16 v[64:79], v[124:127], v[178:181], v[64:79]
	v_sub_f32_e32 v84, v85, v252
	v_exp_f32_e32 v130, v84
	v_lshlrev_b64 v[84:85], v212, s[48:49]
	v_lshl_add_u64 v[84:85], v[84:85], 1, v[230:231]
	s_mov_b32 s12, m0
	s_mov_b32 m0, s67
	s_nop 0
	global_load_lds_dwordx4 v[84:85], off
	s_mov_b32 m0, s12
	v_add_f32_e32 v83, v131, v83
	ds_read_b128 v[120:123], v242 offset:32896
	ds_read_b128 v[124:127], v242 offset:45184
	s_waitcnt lgkmcnt(3)
	v_mfma_f32_32x32x16_bf16 v[96:111], v[112:115], v[174:177], v[96:111]
	v_sub_f32_e32 v84, v86, v252
	v_exp_f32_e32 v131, v84
	v_add_f32_e32 v84, v132, v83
	v_cvt_pk_bf16_f32 v83, v132, v133
	s_waitcnt lgkmcnt(2)
	v_mfma_f32_32x32x16_bf16 v[64:79], v[116:119], v[174:177], v[64:79]
	v_sub_f32_e32 v85, v87, v252
	v_exp_f32_e32 v132, v85
	v_add_f32_e32 v84, v133, v84
	ds_read_b128 v[112:115], v244 offset:32896
	ds_read_b128 v[116:119], v244 offset:45184
	s_waitcnt lgkmcnt(3)
	v_mfma_f32_32x32x16_bf16 v[96:111], v[120:123], v[170:173], v[96:111]
	v_sub_f32_e32 v85, v88, v252
	v_exp_f32_e32 v133, v85
	v_add_f32_e32 v85, v134, v84
	v_cvt_pk_bf16_f32 v84, v134, v135
	s_waitcnt lgkmcnt(2)
	v_mfma_f32_32x32x16_bf16 v[64:79], v[124:127], v[170:173], v[64:79]
	v_sub_f32_e32 v86, v89, v252
	v_exp_f32_e32 v126, v86
	v_lshlrev_b64 v[86:87], v214, s[48:49]
	v_lshl_add_u64 v[86:87], v[86:87], 1, v[232:233]
	s_mov_b32 s12, m0
	s_mov_b32 m0, s68
	s_nop 0
	global_load_lds_dwordx4 v[86:87], off
	s_mov_b32 m0, s12
	v_add_f32_e32 v85, v135, v85
	ds_read_b128 v[86:89], v246 offset:32896
	ds_read_b128 v[120:123], v246 offset:45184
	s_waitcnt lgkmcnt(3)
	v_mfma_f32_32x32x16_bf16 v[96:111], v[112:115], v[166:169], v[96:111]
	v_sub_f32_e32 v90, v90, v252
	v_exp_f32_e32 v127, v90
	v_add_f32_e32 v90, v136, v85
	v_cvt_pk_bf16_f32 v85, v136, v137
	s_waitcnt lgkmcnt(2)
	v_mfma_f32_32x32x16_bf16 v[64:79], v[116:119], v[166:169], v[64:79]
	v_sub_f32_e32 v91, v91, v252
	v_exp_f32_e32 v134, v91
	v_add_f32_e32 v90, v137, v90
	ds_read_b128 v[112:115], v248 offset:32896
	ds_read_b128 v[116:119], v248 offset:45184
	s_waitcnt lgkmcnt(3)
	v_mfma_f32_32x32x16_bf16 v[96:111], v[86:89], v[162:165], v[96:111]
	v_sub_f32_e32 v86, v92, v252
	v_exp_f32_e32 v135, v86
	v_add_f32_e32 v87, v138, v90
	v_cvt_pk_bf16_f32 v86, v138, v139
	s_waitcnt lgkmcnt(2)
	v_mfma_f32_32x32x16_bf16 v[64:79], v[120:123], v[162:165], v[64:79]
	s_mov_b32 s12, m0
	s_mov_b32 m0, s69
	s_nop 0
	global_load_lds_dwordx4 v211, s[42:43]
	s_mov_b32 m0, s12
	v_sub_f32_e32 v88, v93, v252
	v_exp_f32_e32 v136, v88
	v_add_f32_e32 v87, v139, v87
	ds_read_b128 v[88:91], v242 offset:33024
	ds_read_b128 v[120:123], v242 offset:45312
	s_waitcnt lgkmcnt(3)
	v_mfma_f32_32x32x16_bf16 v[96:111], v[112:115], v[158:161], v[96:111]
	v_sub_f32_e32 v92, v94, v252
	v_exp_f32_e32 v137, v92
	v_add_f32_e32 v92, v140, v87
	v_cvt_pk_bf16_f32 v87, v140, v141
	s_waitcnt lgkmcnt(2)
	v_mfma_f32_32x32x16_bf16 v[64:79], v[116:119], v[158:161], v[64:79]
	v_sub_f32_e32 v93, v95, v252
	v_exp_f32_e32 v138, v93
	v_add_f32_e32 v139, v141, v92
	ds_read_b128 v[92:95], v244 offset:33024
	ds_read_b128 v[114:117], v244 offset:45312
	s_waitcnt lgkmcnt(3)
	v_mfma_f32_32x32x16_bf16 v[96:111], v[88:91], v[154:157], v[96:111]
	v_add_f32_e32 v88, v194, v195
	v_add_f32_e32 v88, v196, v88
	v_add_f32_e32 v90, v128, v88
	v_cvt_pk_bf16_f32 v88, v194, v195
	v_cvt_pk_bf16_f32 v89, v196, v128
	v_permlane32_swap_b32_e32 v80, v82
	v_permlane32_swap_b32_e32 v81, v83
	s_waitcnt lgkmcnt(2)
	v_mfma_f32_32x32x16_bf16 v[64:79], v[120:123], v[154:157], v[64:79]
	v_add_f32_e32 v90, v129, v90
	s_mov_b32 s12, m0
	s_mov_b32 m0, s70
	s_nop 0
	global_load_lds_dwordx4 v213, s[42:43]
	s_mov_b32 m0, s12
	v_add_f32_e32 v90, v130, v90
	v_add_f32_e32 v90, v131, v90
	v_add_f32_e32 v112, v132, v90
	v_cvt_pk_bf16_f32 v90, v129, v130
	v_cvt_pk_bf16_f32 v91, v131, v132
	v_permlane32_swap_b32_e32 v84, v86
	v_permlane32_swap_b32_e32 v85, v87
	ds_read_b128 v[118:121], v246 offset:33024
	ds_read_b128 v[122:125], v246 offset:45312
	s_waitcnt lgkmcnt(3)
; template <bool FIN, bool PRE, int DM, class Dma> __device__ __forceinline__ void region_qk(f32x16& ps0, f32x16& ps1, const char* Ks, const bf16x8* qr, const char* qslot, const int (&kb)[4], ...
;     bf16x8 kf[2][2], qf[2]; FinSt st;
;     ...
;     QKT_RD(0, 0);
;     sfor<0, 12>([&](auto d_) { constexpr int d0 = decltype(d_)::value, cb = d0 & 1, nb = cb ^ 1;
;         if constexpr (d0 < 11) QKT_RD(d0 + 1, nb);
;         if constexpr (d0 == 0) ps0 = __builtin_amdgcn_mfma_f32_32x32x16_bf16(kf[cb][0], qf[cb], f32x16{}, 0, 0, 0);
;         else ps0 = __builtin_amdgcn_mfma_f32_32x32x16_bf16(kf[cb][0], qf[cb], ps0, 0, 0, 0);
;         if constexpr (FIN) fin_slice<2 * d0>(pf0, pf1, mreg, alpha, l_reg, st, pa);
;         if constexpr (PRE && d0 >= 10) { constexpr int k = 2 * (d0 - 10); l[k] = tr_read<v_rd_off(0, k, 0)>(vb); h[k] = tr_read<v_rd_off(0, k, 1)>(vb); }
;         __builtin_amdgcn_sched_group_barrier(0x100, 3, 0); __builtin_amdgcn_sched_group_barrier(0x8, 1, 0);
;         SBAR();
;         if constexpr (d0 == 0) ps1 = __builtin_amdgcn_mfma_f32_32x32x16_bf16(kf[cb][1], qf[cb], f32x16{}, 0, 0, 0);
;         else ps1 = __builtin_amdgcn_mfma_f32_32x32x16_bf16(kf[cb][1], qf[cb], ps1, 0, 0, 0);
;         if constexpr (FIN) fin_slice<2 * d0 + 1>(pf0, pf1, mreg, alpha, l_reg, st, pa);
;         if constexpr (PRE && d0 >= 10) { constexpr int k = 2 * (d0 - 10) + 1; l[k] = tr_read<v_rd_off(0, k, 0)>(vb); h[k] = tr_read<v_rd_off(0, k, 1)>(vb); }
;         if constexpr ((d0 & 1) == 0 && d0 < 10 && (DM == 1 || (DM == 2 && d0 >= 6))) dma(std::integral_constant<int, d0 / 2>{});
;         __builtin_amdgcn_sched_group_barrier(0x8, 1, 0);
;         SBAR();
;     });
;     ...
; }
; template <bool PSM, bool PRE> __device__ __forceinline__ void region_pv(f32x16* o, int vb, const bf16x8 (&pa)[4], f32x16& pn0, f32x16& pn1, float& m_reg, float& alpha, s16x4 (&l)[4], s16x4 (&h)[4]) {
;     PsmSt st;
;     if constexpr (!PRE) {
;     l[0] = tr_read<v_rd_off(0, 0, 0)>(vb); h[0] = tr_read<v_rd_off(0, 0, 1)>(vb); l[1] = tr_read<v_rd_off(0, 1, 0)>(vb); h[1] = tr_read<v_rd_off(0, 1, 1)>(vb);
;     l[2] = tr_read<v_rd_off(0, 2, 0)>(vb); h[2] = tr_read<v_rd_off(0, 2, 1)>(vb); l[3] = tr_read<v_rd_off(0, 3, 0)>(vb); h[3] = tr_read<v_rd_off(0, 3, 1)>(vb);
;     SBAR(); }
;     sfor<0, 16>([&](auto n_) { constexpr int n = decltype(n_)::value, b = n >> 2, k = n & 3;
	v_mfma_f32_32x32x16_bf16 v[96:111], v[92:95], v[150:153], v[96:111]
	v_add_f32_e32 v92, v133, v112
	v_add_f32_e32 v92, v126, v92
	v_add_f32_e32 v92, v127, v92
	v_add_f32_e32 v92, v134, v92
	v_cvt_pk_bf16_f32 v112, v133, v126
	v_cvt_pk_bf16_f32 v113, v127, v134
	s_waitcnt lgkmcnt(2)
	v_mfma_f32_32x32x16_bf16 v[64:79], v[114:117], v[150:153], v[64:79]
	v_add_f32_e32 v92, v135, v92
	v_add_f32_e32 v92, v136, v92
	v_add_f32_e32 v92, v137, v92
	v_add_f32_e32 v130, v138, v92
	v_cvt_pk_bf16_f32 v114, v135, v136
	v_cvt_pk_bf16_f32 v115, v137, v138
	ds_read_b128 v[92:95], v248 offset:33024
	ds_read_b128 v[126:129], v248 offset:45312
	ds_read_b64_tr_b16 v[116:117], v251 offset:16384
	s_waitcnt lgkmcnt(4)
	v_mfma_f32_32x32x16_bf16 v[96:111], v[118:121], v[146:149], v[96:111]
	ds_read_b64_tr_b16 v[118:119], v251 offset:18432
	v_permlane32_swap_b32_e32 v88, v90
	v_permlane32_swap_b32_e32 v89, v91
	s_waitcnt lgkmcnt(4)
	v_mfma_f32_32x32x16_bf16 v[64:79], v[122:125], v[146:149], v[64:79]
	ds_read_b64_tr_b16 v[120:121], v251 offset:20480
	ds_read_b64_tr_b16 v[122:123], v251 offset:22528
	v_permlane32_swap_b32_e32 v112, v114
	v_permlane32_swap_b32_e32 v113, v115
	ds_read_b64_tr_b16 v[132:133], v251 offset:26624
	s_waitcnt lgkmcnt(6)
	v_mfma_f32_32x32x16_bf16 v[96:111], v[92:95], v[142:145], v[96:111]
	v_add_f32_e32 v92, v139, v130
	ds_read_b64_tr_b16 v[130:131], v251 offset:24576
	v_mov_b32_e32 v93, v92
	s_nop 1
	v_permlane32_swap_b32_e32 v92, v93
	s_waitcnt lgkmcnt(6)
	v_mfma_f32_32x32x16_bf16 v[64:79], v[126:129], v[142:145], v[64:79]
	ds_read_b64_tr_b16 v[124:125], v251 offset:28672
	ds_read_b64_tr_b16 v[126:127], v251 offset:30720
	s_waitcnt lgkmcnt(6)
	v_mfma_f32_32x32x16_bf16 v[0:15], v[80:83], v[116:119], v[0:15]
	v_max3_f32 v94, v96, v97, v98
	v_max3_f32 v94, v94, v99, v100
	v_max3_f32 v94, v94, v101, v102
	ds_read_b64_tr_b16 v[116:117], v251 offset:16896
	ds_read_b64_tr_b16 v[118:119], v251 offset:18944
	v_max3_f32 v94, v94, v103, v104
	v_max3_f32 v94, v94, v105, v106
	v_max3_f32 v94, v94, v107, v108
	v_max3_f32 v94, v94, v109, v110
	v_max_f32_e32 v95, v65, v65
	v_max_f32_e32 v128, v64, v64
	s_waitcnt lgkmcnt(6)
	v_mfma_f32_32x32x16_bf16 v[0:15], v[84:87], v[120:123], v[0:15]
	v_max_f32_e32 v95, v128, v95
	v_max3_f32 v95, v95, v66, v67
	v_max3_f32 v95, v95, v68, v69
	v_max3_f32 v95, v95, v70, v71
	ds_read_b64_tr_b16 v[120:121], v251 offset:20992
	ds_read_b64_tr_b16 v[122:123], v251 offset:23040
	v_max3_f32 v95, v95, v72, v73
	v_max3_f32 v95, v95, v74, v75
	v_max3_f32 v95, v95, v76, v77
	v_max3_f32 v95, v95, v78, v79
	v_max3_f32 v94, v94, v111, v95
	v_mov_b32_e32 v95, v94
	s_waitcnt lgkmcnt(6)
	v_mfma_f32_32x32x16_bf16 v[0:15], v[88:91], v[130:133], v[0:15]
	v_permlane32_swap_b32_e32 v94, v95
	v_max_f32_e32 v94, v94, v95
	v_sub_f32_e32 v95, v94, v252
	ds_read_b64_tr_b16 v[132:133], v251 offset:25088
	ds_read_b64_tr_b16 v[134:135], v251 offset:27136
	v_cmp_ge_f32_e32 vcc, s33, v95
	s_cmp_eq_u64 vcc, exec
	s_cselect_b64 vcc, -1, 0
	v_max_f32_e32 v94, v252, v94
	v_cndmask_b32_e32 v130, v94, v252, vcc
	s_waitcnt lgkmcnt(6)
	v_mfma_f32_32x32x16_bf16 v[0:15], v[112:115], v[124:127], v[0:15]
	v_sub_f32_e32 v94, v252, v130
	ds_read_b64_tr_b16 v[124:125], v251 offset:29184
	ds_read_b64_tr_b16 v[126:127], v251 offset:31232
	v_exp_f32_e32 v131, v94
	s_waitcnt lgkmcnt(6)
	v_mfma_f32_32x32x16_bf16 v[48:63], v[80:83], v[116:119], v[48:63]
	v_sub_f32_e32 v94, v96, v130
	v_sub_f32_e32 v95, v97, v130
	ds_read_b64_tr_b16 v[116:117], v251 offset:17408
	ds_read_b64_tr_b16 v[118:119], v251 offset:19456
	v_exp_f32_e32 v94, v94
	v_exp_f32_e32 v95, v95
	s_waitcnt lgkmcnt(6)
	v_mfma_f32_32x32x16_bf16 v[48:63], v[84:87], v[120:123], v[48:63]
	v_sub_f32_e32 v96, v98, v130
	v_sub_f32_e32 v97, v99, v130
	ds_read_b64_tr_b16 v[120:121], v251 offset:21504
	ds_read_b64_tr_b16 v[122:123], v251 offset:23552
	v_exp_f32_e32 v96, v96
	v_exp_f32_e32 v97, v97
	s_waitcnt lgkmcnt(6)
	v_mfma_f32_32x32x16_bf16 v[48:63], v[88:91], v[132:135], v[48:63]
	v_sub_f32_e32 v98, v100, v130
	v_sub_f32_e32 v99, v101, v130
	ds_read_b64_tr_b16 v[132:133], v251 offset:25600
	ds_read_b64_tr_b16 v[134:135], v251 offset:27648
	v_exp_f32_e32 v98, v98
	v_exp_f32_e32 v99, v99
	s_waitcnt lgkmcnt(6)
	v_mfma_f32_32x32x16_bf16 v[48:63], v[112:115], v[124:127], v[48:63]
	v_sub_f32_e32 v100, v102, v130
	v_sub_f32_e32 v101, v103, v130
	ds_read_b64_tr_b16 v[124:125], v251 offset:29696
	ds_read_b64_tr_b16 v[126:127], v251 offset:31744
	v_exp_f32_e32 v100, v100
	v_exp_f32_e32 v101, v101
	s_waitcnt lgkmcnt(6)
	v_mfma_f32_32x32x16_bf16 v[32:47], v[80:83], v[116:119], v[32:47]
	v_sub_f32_e32 v102, v104, v130
	ds_read_b64_tr_b16 v[116:117], v251 offset:17920
	ds_read_b64_tr_b16 v[118:119], v251 offset:19968
	v_exp_f32_e32 v102, v102
	s_waitcnt lgkmcnt(6)
	v_mfma_f32_32x32x16_bf16 v[32:47], v[84:87], v[120:123], v[32:47]
	v_sub_f32_e32 v103, v105, v130
	ds_read_b64_tr_b16 v[120:121], v251 offset:22016
	ds_read_b64_tr_b16 v[122:123], v251 offset:24064
	v_exp_f32_e32 v103, v103
	s_waitcnt lgkmcnt(6)
	v_mfma_f32_32x32x16_bf16 v[32:47], v[88:91], v[132:135], v[32:47]
	v_sub_f32_e32 v104, v106, v130
	ds_read_b64_tr_b16 v[132:133], v251 offset:26112
	ds_read_b64_tr_b16 v[134:135], v251 offset:28160
	v_exp_f32_e32 v104, v104
	s_waitcnt lgkmcnt(6)
	v_mfma_f32_32x32x16_bf16 v[32:47], v[112:115], v[124:127], v[32:47]
	v_sub_f32_e32 v105, v107, v130
	ds_read_b64_tr_b16 v[124:125], v251 offset:30208
	ds_read_b64_tr_b16 v[126:127], v251 offset:32256
	v_exp_f32_e32 v105, v105
	s_waitcnt lgkmcnt(6)
	v_mfma_f32_32x32x16_bf16 v[16:31], v[80:83], v[116:119], v[16:31]
	v_sub_f32_e32 v80, v108, v130
	v_exp_f32_e32 v106, v80
	s_waitcnt lgkmcnt(4)
	v_mfma_f32_32x32x16_bf16 v[16:31], v[84:87], v[120:123], v[16:31]
	v_sub_f32_e32 v80, v109, v130
	v_exp_f32_e32 v107, v80
	s_waitcnt lgkmcnt(2)
	v_mfma_f32_32x32x16_bf16 v[16:31], v[88:91], v[132:135], v[16:31]
	v_sub_f32_e32 v80, v110, v130
	v_exp_f32_e32 v108, v80
	s_waitcnt lgkmcnt(0)
	v_mfma_f32_32x32x16_bf16 v[16:31], v[112:115], v[124:127], v[16:31]
	v_sub_f32_e32 v80, v111, v130
	v_exp_f32_e32 v109, v80
	v_cmp_gt_f32_e32 vcc, 1.0, v131
	s_cbranch_vccz .LBB0_632
	s_and_saveexec_b64 s[48:49], s[40:41]
	ds_write_b32 v215, v131 offset:128
	s_or_b64 exec, exec, s[48:49]
	s_waitcnt lgkmcnt(0)
	ds_read_b128 v[80:83], v250 offset:224
	ds_read_b128 v[84:87], v250 offset:192
	ds_read_b128 v[88:91], v250 offset:160
	ds_read_b128 v[110:113], v250 offset:128
	s_waitcnt lgkmcnt(3)
	v_pk_mul_f32 v[14:15], v[14:15], v[82:83]
	s_waitcnt lgkmcnt(2)
	v_pk_mul_f32 v[10:11], v[10:11], v[86:87]
	s_waitcnt lgkmcnt(1)
	v_pk_mul_f32 v[6:7], v[6:7], v[90:91]
	s_waitcnt lgkmcnt(0)
	v_pk_mul_f32 v[2:3], v[2:3], v[112:113]
	v_pk_mul_f32 v[12:13], v[12:13], v[80:81]
	v_pk_mul_f32 v[8:9], v[8:9], v[84:85]
	v_pk_mul_f32 v[4:5], v[4:5], v[88:89]
	v_pk_mul_f32 v[0:1], v[0:1], v[110:111]
	v_pk_mul_f32 v[62:63], v[62:63], v[82:83]
	v_pk_mul_f32 v[58:59], v[58:59], v[86:87]
	v_pk_mul_f32 v[54:55], v[54:55], v[90:91]
	v_pk_mul_f32 v[50:51], v[50:51], v[112:113]
	v_pk_mul_f32 v[60:61], v[60:61], v[80:81]
	v_pk_mul_f32 v[56:57], v[56:57], v[84:85]
	v_pk_mul_f32 v[52:53], v[52:53], v[88:89]
	v_pk_mul_f32 v[48:49], v[48:49], v[110:111]
	v_pk_mul_f32 v[46:47], v[46:47], v[82:83]
	v_pk_mul_f32 v[42:43], v[42:43], v[86:87]
	v_pk_mul_f32 v[38:39], v[38:39], v[90:91]
	v_pk_mul_f32 v[34:35], v[34:35], v[112:113]
	v_pk_mul_f32 v[44:45], v[44:45], v[80:81]
	v_pk_mul_f32 v[40:41], v[40:41], v[84:85]
	v_pk_mul_f32 v[36:37], v[36:37], v[88:89]
	v_pk_mul_f32 v[32:33], v[32:33], v[110:111]
	v_pk_mul_f32 v[30:31], v[30:31], v[82:83]
	v_pk_mul_f32 v[26:27], v[26:27], v[86:87]
	v_pk_mul_f32 v[22:23], v[22:23], v[90:91]
	v_pk_mul_f32 v[18:19], v[18:19], v[112:113]
	v_pk_mul_f32 v[28:29], v[28:29], v[80:81]
	v_pk_mul_f32 v[24:25], v[24:25], v[84:85]
	v_pk_mul_f32 v[20:21], v[20:21], v[88:89]
	v_pk_mul_f32 v[16:17], v[16:17], v[110:111]
	.p2align 6
